# tile-order step of the persistent GEMM loop computed incrementally from the current tile (about 20 scalar ops instead of about 90 with two emulated divisions); generic path kept behind a gridDim==256
# speedup vs baseline: 1.0165x; 1.0023x over previous
.LBB0_124:
	s_add_i32 s58, s58, 1
	s_cmp_lg_u32 s72, 0x100
	s_cbranch_scc1 .Lnext_generic
	s_lshr_b32 s42, s90, 3
	s_cmp_lt_u32 s58, s42
	s_cselect_b64 s[44:45], -1, 0
	s_and_b32 s55, s69, 7
	s_lshl_b32 s68, s54, 3
	s_add_i32 s68, s68, s55
	s_add_i32 s68, s68, 32
	s_lshr_b32 s56, s69, 3
	s_cmp_ge_u32 s68, s90
	s_cselect_b32 s57, s90, 0
	s_cselect_b32 s74, 1, 0
	s_sub_i32 s68, s68, s57
	s_add_i32 s56, s56, s74
	s_lshl_b32 s56, s56, 3
	s_add_i32 s55, s56, s55
	s_lshr_b32 s68, s68, 3
	s_branch .LBB0_126
.Lnext_generic:
	v_readlane_b32 s42, v254, 52
	s_mul_i32 s42, s58, s42
	s_mul_hi_u32 s43, s58, s72
	s_add_i32 s43, s43, s42
	s_mul_i32 s42, s58, s72
	s_add_u32 s42, s42, s91
	s_addc_u32 s43, s43, s59
	v_mov_b64_e32 v[2:3], s[24:25]
	v_cmp_ge_i64_e32 vcc, s[42:43], v[2:3]
	v_cmp_lt_i64_e64 s[44:45], s[42:43], v[2:3]
	s_cbranch_vccnz .LBB0_126
	s_ashr_i32 s43, s42, 31
	s_lshr_b32 s43, s43, 29
	s_add_i32 s43, s42, s43
	s_ashr_i32 s55, s43, 3
	s_and_b32 s43, s43, -8
	s_sub_i32 s42, s42, s43
	s_lshr_b32 s43, s42, 31
	s_or_b32 s43, s46, s43
	s_mul_i32 s42, s43, s42
	s_add_i32 s42, s42, s55
	s_abs_i32 s55, s42
	s_mul_hi_u32 s56, s55, s47
	s_mul_i32 s57, s56, s90
	s_sub_i32 s55, s55, s57
	s_ashr_i32 s43, s42, 31
	s_add_i32 s57, s56, 1
	s_sub_i32 s68, s55, s90
	s_cmp_ge_u32 s55, s90
	s_cselect_b32 s56, s57, s56
	s_cselect_b32 s55, s68, s55
	s_add_i32 s57, s56, 1
	s_cmp_ge_u32 s55, s90
	s_cselect_b32 s55, s57, s56
	s_xor_b32 s55, s55, s43
	s_sub_i32 s43, s55, s43
	s_lshl_b32 s55, s43, 3
	s_sub_i32 s56, 0x100, s55
	s_min_i32 s56, s56, 8
	s_abs_i32 s57, s56
	v_cvt_f32_u32_e32 v2, s57
	s_sub_i32 s74, 0, s57
	s_mul_i32 s43, s43, s90
	s_sub_i32 s42, s42, s43
	v_rcp_iflag_f32_e32 v2, v2
	s_abs_i32 s68, s42
	s_xor_b32 s43, s42, s56
	s_ashr_i32 s43, s43, 31
	v_mul_f32_e32 v2, 0x4f7ffffe, v2
	v_cvt_u32_f32_e32 v2, v2
	s_nop 0
	v_readfirstlane_b32 s75, v2
	s_mul_i32 s74, s74, s75
	s_mul_hi_u32 s74, s75, s74
	s_add_i32 s75, s75, s74
	s_mul_hi_u32 s74, s68, s75
	s_mul_i32 s75, s74, s57
	s_sub_i32 s68, s68, s75
	s_add_i32 s75, s74, 1
	s_sub_i32 s92, s68, s57
	s_cmp_ge_u32 s68, s57
	s_cselect_b32 s74, s75, s74
	s_cselect_b32 s68, s92, s68
	s_add_i32 s75, s74, 1
	s_cmp_ge_u32 s68, s57
	s_cselect_b32 s57, s75, s74
	s_xor_b32 s57, s57, s43
	s_sub_i32 s68, s57, s43
	s_mul_i32 s43, s68, s56
	s_sub_i32 s42, s42, s43
	s_add_i32 s55, s42, s55
